# tile tail: spacer between v_cmpx and the masked flag write (same schedule otherwise)
# baseline (speedup 1.0000x reference)
.LBB0_579:
	s_mul_i32 s0, s68, 0x2400
	v_add_u32_e32 v8, s0, v199
	ds_read_b128 v[0:3], v8
	ds_read_b128 v[4:7], v8 offset:32
	s_cmp_lt_i32 s9, s17
	s_cselect_b64 s[50:51], -1, 0
	v_cndmask_b32_e64 v176, v223, v212, s[50:51]
	s_waitcnt lgkmcnt(0)
	v_mfma_f32_32x32x16_bf16 v[48:63], v[72:75], v[0:3], 0
	v_add_u32_e32 v177, s66, v227
	v_add_u32_e32 v180, 32, v228
	v_mfma_f32_32x32x16_bf16 v[32:47], v[88:91], v[0:3], 0
	v_mfma_f32_32x32x16_bf16 v[48:63], v[76:79], v[4:7], v[48:63]
	v_mfma_f32_32x32x16_bf16 v[32:47], v[92:95], v[4:7], v[32:47]
	ds_read_b128 v[0:3], v8 offset:64
	ds_read_b128 v[4:7], v8 offset:96
	ds_read_b128 v[112:115], v8 offset:4672
	ds_read_b128 v[108:111], v8 offset:4704
	s_waitcnt lgkmcnt(0)
	v_mfma_f32_32x32x16_bf16 v[48:63], v[80:83], v[0:3], v[48:63]
	v_mfma_f32_32x32x16_bf16 v[48:63], v[84:87], v[4:7], v[48:63]
	v_mfma_f32_32x32x16_bf16 v[32:47], v[96:99], v[0:3], v[32:47]
	ds_read_b128 v[116:119], v8 offset:4640
	ds_read_b128 v[0:3], v8 offset:4608
	s_nop 8
	v_add_f32_e64 v8, v48, |v48|
	v_fma_f32 v48, v142, v8, 0
	v_add_f32_e64 v8, v49, |v49|
	v_fmac_f32_e32 v48, v143, v8
	v_add_f32_e64 v8, v50, |v50|
	v_fmac_f32_e32 v48, v140, v8
	v_mfma_f32_32x32x16_bf16 v[32:47], v[100:103], v[4:7], v[32:47]
	v_add_f32_e64 v4, v51, |v51|
	v_fmac_f32_e32 v48, v141, v4
	v_add_f32_e64 v4, v52, |v52|
	v_fmac_f32_e32 v48, v146, v4
	v_add_f32_e64 v4, v53, |v53|
	v_fmac_f32_e32 v48, v147, v4
	v_add_f32_e64 v4, v54, |v54|
	v_fmac_f32_e32 v48, v144, v4
	v_add_f32_e64 v4, v55, |v55|
	s_waitcnt lgkmcnt(0)
	v_mfma_f32_32x32x16_bf16 v[16:31], v[72:75], v[0:3], 0
	v_fmac_f32_e32 v48, v145, v4
	v_mfma_f32_32x32x16_bf16 v[0:15], v[88:91], v[0:3], 0
	v_cmp_le_i32_e32 vcc, v177, v176
	v_ashrrev_i32_e32 v247, 31, v48
	v_bitop3_b32 v244, v247, v48, s93 bitop3:0x36
	v_cndmask_b32_e32 v246, v214, v48, vcc
	v_cmpx_ge_f32_e32 vcc, v246, v188
	v_and_or_b32 v244, v244, s80, v180
	s_nop 0
	v_and_b32_e32 v247, vcc_lo, v242
	v_mbcnt_lo_u32_b32 v243, v247, 0
	v_mbcnt_hi_u32_b32 v243, vcc_hi, v243
	v_lshl_add_u32 v245, v243, 2, v238
	ds_write_b32 v245, v244
	s_mov_b64 exec, -1
	v_bcnt_u32_b32 v246, vcc_lo, 0
	v_bcnt_u32_b32 v247, vcc_hi, 0
	v_cndmask_b32_e64 v246, v247, v246, s[40:41]
	v_lshl_add_u32 v238, v246, 2, v238
	v_add_f32_e64 v50, v56, |v56|
	v_fma_f32 v50, v150, v50, 0
	v_add_f32_e64 v51, v57, |v57|
	v_fmac_f32_e32 v50, v151, v51
	v_add_f32_e64 v51, v58, |v58|
	v_fmac_f32_e32 v50, v148, v51
	v_add_f32_e64 v51, v59, |v59|
	v_mfma_f32_32x32x16_bf16 v[16:31], v[76:79], v[116:119], v[16:31]
	v_fmac_f32_e32 v50, v149, v51
	v_add_f32_e64 v51, v60, |v60|
	v_fmac_f32_e32 v50, v154, v51
	v_add_f32_e64 v51, v61, |v61|
	v_fmac_f32_e32 v50, v155, v51
	v_add_f32_e64 v51, v62, |v62|
	v_fmac_f32_e32 v50, v152, v51
	v_mfma_f32_32x32x16_bf16 v[0:15], v[92:95], v[116:119], v[0:15]
	v_add_f32_e64 v51, v63, |v63|
	v_cndmask_b32_e64 v48, v224, v212, s[50:51]
	v_fmac_f32_e32 v50, v153, v51
	v_cmp_le_i32_e32 vcc, v177, v48
	v_ashrrev_i32_e32 v247, 31, v50
	v_bitop3_b32 v244, v247, v50, s93 bitop3:0x36
	v_cndmask_b32_e32 v246, v214, v50, vcc
	v_cmpx_ge_f32_e32 vcc, v246, v189
	v_and_or_b32 v244, v244, s80, v180
	s_nop 0
	v_and_b32_e32 v247, vcc_lo, v242
	v_mbcnt_lo_u32_b32 v243, v247, 0
	v_mbcnt_hi_u32_b32 v243, vcc_hi, v243
	v_lshl_add_u32 v245, v243, 2, v239
	ds_write_b32 v245, v244
	s_mov_b64 exec, -1
	v_bcnt_u32_b32 v246, vcc_lo, 0
	v_bcnt_u32_b32 v247, vcc_hi, 0
	v_cndmask_b32_e64 v246, v247, v246, s[40:41]
	v_lshl_add_u32 v239, v246, 2, v239
	v_add_f32_e64 v32, v32, |v32|
	v_fma_f32 v32, v158, v32, 0
	v_add_f32_e64 v33, v33, |v33|
	v_fmac_f32_e32 v32, v159, v33
	v_add_f32_e64 v33, v34, |v34|
	v_fmac_f32_e32 v32, v156, v33
	v_add_f32_e64 v33, v35, |v35|
	v_mfma_f32_32x32x16_bf16 v[16:31], v[80:83], v[112:115], v[16:31]
	v_fmac_f32_e32 v32, v157, v33
	v_add_f32_e64 v33, v36, |v36|
	v_fmac_f32_e32 v32, v162, v33
	v_add_f32_e64 v33, v37, |v37|
	v_fmac_f32_e32 v32, v163, v33
	v_add_f32_e64 v33, v38, |v38|
	v_fmac_f32_e32 v32, v160, v33
	v_mfma_f32_32x32x16_bf16 v[0:15], v[96:99], v[112:115], v[0:15]
	v_add_f32_e64 v33, v39, |v39|
	v_cndmask_b32_e64 v50, v225, v212, s[50:51]
	v_fmac_f32_e32 v32, v161, v33
	v_cmp_le_i32_e32 vcc, v177, v50
	v_ashrrev_i32_e32 v247, 31, v32
	v_bitop3_b32 v244, v247, v32, s93 bitop3:0x36
	v_cndmask_b32_e32 v246, v214, v32, vcc
	v_cmpx_ge_f32_e32 vcc, v246, v190
	v_and_or_b32 v244, v244, s80, v180
	s_nop 0
	v_and_b32_e32 v247, vcc_lo, v242
	v_mbcnt_lo_u32_b32 v243, v247, 0
	v_mbcnt_hi_u32_b32 v243, vcc_hi, v243
	v_lshl_add_u32 v245, v243, 2, v240
	ds_write_b32 v245, v244
	s_mov_b64 exec, -1
	v_bcnt_u32_b32 v246, vcc_lo, 0
	v_bcnt_u32_b32 v247, vcc_hi, 0
	v_cndmask_b32_e64 v246, v247, v246, s[40:41]
	v_lshl_add_u32 v240, v246, 2, v240
	v_add_f32_e64 v34, v40, |v40|
	v_fma_f32 v35, v166, v34, 0
	v_add_f32_e64 v34, v41, |v41|
	v_fmac_f32_e32 v35, v167, v34
	v_add_f32_e64 v34, v42, |v42|
	v_fmac_f32_e32 v35, v164, v34
	v_add_f32_e64 v34, v43, |v43|
	v_mfma_f32_32x32x16_bf16 v[16:31], v[84:87], v[108:111], v[16:31]
	v_fmac_f32_e32 v35, v165, v34
	v_add_f32_e64 v34, v44, |v44|
	v_fmac_f32_e32 v35, v170, v34
	v_add_f32_e64 v34, v45, |v45|
	v_fmac_f32_e32 v35, v171, v34
	v_add_f32_e64 v34, v46, |v46|
	v_fmac_f32_e32 v35, v168, v34
	v_mfma_f32_32x32x16_bf16 v[0:15], v[100:103], v[108:111], v[0:15]
	v_add_f32_e64 v34, v47, |v47|
	v_cndmask_b32_e64 v32, v226, v212, s[50:51]
	v_fmac_f32_e32 v35, v169, v34
	v_cmp_le_i32_e32 vcc, v177, v32
	v_ashrrev_i32_e32 v247, 31, v35
	v_bitop3_b32 v244, v247, v35, s93 bitop3:0x36
	v_cndmask_b32_e32 v246, v214, v35, vcc
	v_cmpx_ge_f32_e32 vcc, v246, v191
	v_and_or_b32 v244, v244, s80, v180
	s_nop 0
	v_and_b32_e32 v247, vcc_lo, v242
	v_mbcnt_lo_u32_b32 v243, v247, 0
	v_mbcnt_hi_u32_b32 v243, vcc_hi, v243
	v_lshl_add_u32 v245, v243, 2, v241
	ds_write_b32 v245, v244
	s_mov_b64 exec, -1
	v_bcnt_u32_b32 v246, vcc_lo, 0
	v_bcnt_u32_b32 v247, vcc_hi, 0
	v_cndmask_b32_e64 v246, v247, v246, s[40:41]
	v_lshl_add_u32 v241, v246, 2, v241
	v_add_f32_e64 v16, v16, |v16|
	v_fma_f32 v16, v142, v16, 0
	v_add_f32_e64 v17, v17, |v17|
	v_fmac_f32_e32 v16, v143, v17
	v_add_f32_e64 v17, v18, |v18|
	v_fmac_f32_e32 v16, v140, v17
	v_add_f32_e64 v17, v19, |v19|
	v_fmac_f32_e32 v16, v141, v17
	v_add_f32_e64 v17, v20, |v20|
	v_fmac_f32_e32 v16, v146, v17
	v_add_f32_e64 v17, v21, |v21|
	v_fmac_f32_e32 v16, v147, v17
	v_add_f32_e64 v17, v22, |v22|
	v_fmac_f32_e32 v16, v144, v17
	v_add_f32_e64 v17, v23, |v23|
	v_add_u32_e32 v35, 32, v177
	v_fmac_f32_e32 v16, v145, v17
	v_cmp_le_i32_e32 vcc, v35, v176
	v_ashrrev_i32_e32 v247, 31, v16
	v_bitop3_b32 v244, v247, v16, s93 bitop3:0x36
	v_cndmask_b32_e32 v246, v214, v16, vcc
	v_cmpx_ge_f32_e32 vcc, v246, v188
	v_and_or_b32 v244, v244, s80, v228
	s_nop 0
	v_and_b32_e32 v247, vcc_lo, v242
	v_mbcnt_lo_u32_b32 v243, v247, 0
	v_mbcnt_hi_u32_b32 v243, vcc_hi, v243
	v_lshl_add_u32 v245, v243, 2, v238
	ds_write_b32 v245, v244
	s_mov_b64 exec, -1
	v_bcnt_u32_b32 v246, vcc_lo, 0
	v_bcnt_u32_b32 v247, vcc_hi, 0
	v_cndmask_b32_e64 v246, v247, v246, s[40:41]
	v_lshl_add_u32 v238, v246, 2, v238
	v_add_f32_e64 v16, v24, |v24|
	v_fma_f32 v16, v150, v16, 0
	v_add_f32_e64 v17, v25, |v25|
	v_fmac_f32_e32 v16, v151, v17
	v_add_f32_e64 v17, v26, |v26|
	v_fmac_f32_e32 v16, v148, v17
	v_add_f32_e64 v17, v27, |v27|
	v_fmac_f32_e32 v16, v149, v17
	v_add_f32_e64 v17, v28, |v28|
	v_fmac_f32_e32 v16, v154, v17
	v_add_f32_e64 v17, v29, |v29|
	v_fmac_f32_e32 v16, v155, v17
	v_add_f32_e64 v17, v30, |v30|
	v_fmac_f32_e32 v16, v152, v17
	v_add_f32_e64 v17, v31, |v31|
	v_fmac_f32_e32 v16, v153, v17
	v_cmp_le_i32_e32 vcc, v35, v48
	v_ashrrev_i32_e32 v247, 31, v16
	v_bitop3_b32 v244, v247, v16, s93 bitop3:0x36
	v_cndmask_b32_e32 v246, v214, v16, vcc
	v_cmpx_ge_f32_e32 vcc, v246, v189
	v_and_or_b32 v244, v244, s80, v228
	s_nop 0
	v_and_b32_e32 v247, vcc_lo, v242
	v_mbcnt_lo_u32_b32 v243, v247, 0
	v_mbcnt_hi_u32_b32 v243, vcc_hi, v243
	v_lshl_add_u32 v245, v243, 2, v239
	ds_write_b32 v245, v244
	s_mov_b64 exec, -1
	v_bcnt_u32_b32 v246, vcc_lo, 0
	v_bcnt_u32_b32 v247, vcc_hi, 0
	v_cndmask_b32_e64 v246, v247, v246, s[40:41]
	v_lshl_add_u32 v239, v246, 2, v239
	v_add_f32_e64 v0, v0, |v0|
	v_fma_f32 v0, v158, v0, 0
	v_add_f32_e64 v1, v1, |v1|
	v_fmac_f32_e32 v0, v159, v1
	v_add_f32_e64 v1, v2, |v2|
	v_fmac_f32_e32 v0, v156, v1
	v_add_f32_e64 v1, v3, |v3|
	v_fmac_f32_e32 v0, v157, v1
	v_add_f32_e64 v1, v4, |v4|
	v_fmac_f32_e32 v0, v162, v1
	v_add_f32_e64 v1, v5, |v5|
	v_fmac_f32_e32 v0, v163, v1
	v_add_f32_e64 v1, v6, |v6|
	v_fmac_f32_e32 v0, v160, v1
	v_add_f32_e64 v1, v7, |v7|
	v_fmac_f32_e32 v0, v161, v1
	v_cmp_le_i32_e32 vcc, v35, v50
	v_ashrrev_i32_e32 v247, 31, v0
	v_bitop3_b32 v244, v247, v0, s93 bitop3:0x36
	v_cndmask_b32_e32 v246, v214, v0, vcc
	v_cmpx_ge_f32_e32 vcc, v246, v190
	v_and_or_b32 v244, v244, s80, v228
	s_nop 0
	v_and_b32_e32 v247, vcc_lo, v242
	v_mbcnt_lo_u32_b32 v243, v247, 0
	v_mbcnt_hi_u32_b32 v243, vcc_hi, v243
	v_lshl_add_u32 v245, v243, 2, v240
	ds_write_b32 v245, v244
	s_mov_b64 exec, -1
	v_bcnt_u32_b32 v246, vcc_lo, 0
	v_bcnt_u32_b32 v247, vcc_hi, 0
	v_cndmask_b32_e64 v246, v247, v246, s[40:41]
	v_lshl_add_u32 v240, v246, 2, v240
	v_add_f32_e64 v0, v8, |v8|
	v_fma_f32 v0, v166, v0, 0
	v_add_f32_e64 v1, v9, |v9|
	v_fmac_f32_e32 v0, v167, v1
	v_add_f32_e64 v1, v10, |v10|
	v_fmac_f32_e32 v0, v164, v1
	v_add_f32_e64 v1, v11, |v11|
	v_fmac_f32_e32 v0, v165, v1
	v_add_f32_e64 v1, v12, |v12|
	v_fmac_f32_e32 v0, v170, v1
	v_add_f32_e64 v1, v13, |v13|
	v_fmac_f32_e32 v0, v171, v1
	v_add_f32_e64 v1, v14, |v14|
	v_fmac_f32_e32 v0, v168, v1
	v_add_f32_e64 v1, v15, |v15|
	v_fmac_f32_e32 v0, v169, v1
	v_cmp_le_i32_e32 vcc, v35, v32
	v_ashrrev_i32_e32 v247, 31, v0
	v_bitop3_b32 v244, v247, v0, s93 bitop3:0x36
	v_cndmask_b32_e32 v246, v214, v0, vcc
	v_cmpx_ge_f32_e32 vcc, v246, v191
	v_and_or_b32 v244, v244, s80, v228
	s_nop 0
	v_and_b32_e32 v247, vcc_lo, v242
	v_mbcnt_lo_u32_b32 v243, v247, 0
	v_mbcnt_hi_u32_b32 v243, vcc_hi, v243
	v_lshl_add_u32 v245, v243, 2, v241
	ds_write_b32 v245, v244
	s_mov_b64 exec, -1
	v_bcnt_u32_b32 v246, vcc_lo, 0
	v_bcnt_u32_b32 v247, vcc_hi, 0
	v_cndmask_b32_e64 v246, v247, v246, s[40:41]
	v_lshl_add_u32 v241, v246, 2, v241
	v_sub_u32_e32 v243, v238, v248
	v_sub_u32_e32 v244, v239, v249
	v_sub_u32_e32 v245, v240, v250
	v_sub_u32_e32 v246, v241, v237
	v_max3_u32 v243, v243, v244, v245
	v_max_u32_e32 v243, v243, v246
	v_mov_b32_e32 v244, s21
	v_mov_b32_e32 v246, s9
	v_cmpx_lt_u32_e32 vcc, 0x700, v243
	v_cmpx_eq_u32_e32 vcc, 0, v172
	v_nop
	ds_write_b32 v244, v246
	s_mov_b64 exec, -1
	s_andn2_b64 vcc, exec, s[2:3]
	s_xor_b32 s68, s68, 1
	s_cbranch_vccnz .Lto_nost
	s_mul_i32 s2, s68, 0x2400
	v_add_u32_e32 v0, s2, v187
	s_waitcnt vmcnt(0)
	ds_write_b128 v0, v[104:107]
